# L2 misc-prep row loop: the 16 split-K partial loads (ik, iw|bg) issued up front with one wait instead of 16 serialized round trips; same f32 summation order
# baseline (speedup 1.0000x reference)
; DI float bf2f(bf16_t b) { return __uint_as_float(((unsigned)b) << 16); }
; DI bf16_t f2bf(float f) { return (bf16_t)(cvtpk(f, 0.f) & 0xffffu); }
; DI float wsum(float v) { for (int o = 32; o; o >>= 1) v += __shfl_xor(v, o); return v; }
; DI float sigm(float x) { return __builtin_amdgcn_rcpf(1.f + __expf(-x)); }
; __global__ void __launch_bounds__(NTHR) fwd_megakernel(Params p) {
;     ...
;       for (int row = gw; row < T; row += nw) {
;         const int pos = row & (SL - 1);
;         { const bf16x8 a = *(const bf16x8*)(hbuf + (size_t)row * NPHYS + H_ALAT + lane * 8); float s = 0;
;           for (int j = 0; j < 8; ++j) { const float v = bf2f((bf16_t)a[j]); s += v * v; }
;           s = wsum(s); if (lane == 0) srow[row] = rsqrtf(s * (1.f / 512.f) + 1e-6f); }
;         { float v = 0.f; for (int k = 0; k < 8; ++k) v += __builtin_nontemporal_load(&miscp[((size_t)k * T + row) * 128 + lane]); const float mu = wsum(v) * (1.f / 64.f); const float d = v - mu; const float var = wsum(d * d) * (1.f / 64.f);
;           const float y = d * rsqrtf(var + 1e-5f);
;           const float y8 = __shfl_xor(y, 8);
;           float o = y;
;           if (lane < 16) { const int f = lane & 7; const float cs = ropeI[pos * 16 + f], sn = ropeI[pos * 16 + 8 + f]; o = lane < 8 ? y * cs - y8 * sn : y * cs + y8 * sn; }
;           ikn[(size_t)row * 64 + lane] = f2bf(o); }
;         { float v = 0.f; for (int k = 0; k < 8; ++k) v += __builtin_nontemporal_load(&miscp[((size_t)k * T + row) * 128 + 64 + lane]);
;           if (lane < 16) iwf[(size_t)row * 16 + lane] = v * (0.25f * 0.125f);
;           else if (lane < 40) bgt[(size_t)row * 24 + (lane - 16)] = sigm(v); }
.LBB0_739:
	v_readlane_b32 s20, v252, 15
	v_readlane_b32 s26, v252, 21
	v_readlane_b32 s27, v252, 22
	v_readlane_b32 s21, v252, 16
	v_readlane_b32 s22, v252, 17
	v_lshl_add_u64 v[14:15], s[26:27], 0, v[12:13]
	global_load_dwordx4 v[26:29], v[14:15], off
	v_lshl_add_u64 v[30:31], s[26:27], 0, v[4:5]
	s_mov_b64 s[16:17], 0x17300000
	v_lshl_add_u64 v[32:33], v[30:31], 0, s[16:17]
	global_load_dword v34, v[32:33], off nt
	global_load_dword v42, v[32:33], off offset:256 nt
	s_mov_b64 s[16:17], 0x17700000
	v_lshl_add_u64 v[32:33], v[30:31], 0, s[16:17]
	global_load_dword v35, v[32:33], off nt
	global_load_dword v43, v[32:33], off offset:256 nt
	s_mov_b64 s[16:17], 0x17b00000
	v_lshl_add_u64 v[32:33], v[30:31], 0, s[16:17]
	global_load_dword v36, v[32:33], off nt
	global_load_dword v44, v[32:33], off offset:256 nt
	s_mov_b64 s[16:17], 0x17f00000
	v_lshl_add_u64 v[32:33], v[30:31], 0, s[16:17]
	global_load_dword v37, v[32:33], off nt
	global_load_dword v45, v[32:33], off offset:256 nt
	s_mov_b64 s[16:17], 0x18300000
	v_lshl_add_u64 v[32:33], v[30:31], 0, s[16:17]
	global_load_dword v38, v[32:33], off nt
	global_load_dword v46, v[32:33], off offset:256 nt
	s_mov_b64 s[16:17], 0x18700000
	v_lshl_add_u64 v[32:33], v[30:31], 0, s[16:17]
	global_load_dword v39, v[32:33], off nt
	global_load_dword v47, v[32:33], off offset:256 nt
	s_mov_b64 s[16:17], 0x18b00000
	v_lshl_add_u64 v[32:33], v[30:31], 0, s[16:17]
	global_load_dword v40, v[32:33], off nt
	global_load_dword v48, v[32:33], off offset:256 nt
	s_mov_b64 s[16:17], 0x18f00000
	v_lshl_add_u64 v[32:33], v[30:31], 0, s[16:17]
	global_load_dword v41, v[32:33], off nt
	global_load_dword v49, v[32:33], off offset:256 nt
	v_readlane_b32 s23, v252, 18
	v_readlane_b32 s24, v252, 19
	v_readlane_b32 s25, v252, 20
	s_waitcnt vmcnt(16)
	v_and_b32_e32 v14, 0xffff0000, v26
	v_lshlrev_b32_e32 v0, 16, v26
	v_mul_f32_e32 v14, v14, v14
	v_fmac_f32_e32 v14, v0, v0
	v_lshlrev_b32_e32 v0, 16, v27
	v_fmac_f32_e32 v14, v0, v0
	v_and_b32_e32 v0, 0xffff0000, v27
	v_fmac_f32_e32 v14, v0, v0
	v_lshlrev_b32_e32 v0, 16, v28
	v_fmac_f32_e32 v14, v0, v0
	v_and_b32_e32 v0, 0xffff0000, v28
	v_fmac_f32_e32 v14, v0, v0
	v_lshlrev_b32_e32 v0, 16, v29
	v_fmac_f32_e32 v14, v0, v0
	v_and_b32_e32 v0, 0xffff0000, v29
	v_fmac_f32_e32 v14, v0, v0
	ds_bpermute_b32 v0, v18, v14
	s_waitcnt lgkmcnt(0)
	v_add_f32_e32 v0, v14, v0
	ds_bpermute_b32 v14, v19, v0
	s_waitcnt lgkmcnt(0)
	v_add_f32_e32 v0, v0, v14
	ds_bpermute_b32 v14, v20, v0
	s_waitcnt lgkmcnt(0)
	v_add_f32_e32 v0, v0, v14
	ds_bpermute_b32 v14, v21, v0
	s_waitcnt lgkmcnt(0)
	v_add_f32_e32 v0, v0, v14
	ds_bpermute_b32 v14, v22, v0
	s_waitcnt lgkmcnt(0)
	v_add_f32_e32 v0, v0, v14
	ds_bpermute_b32 v14, v23, v0
	s_and_saveexec_b64 s[14:15], s[0:1]
	s_cbranch_execz .LBB0_741
	s_waitcnt lgkmcnt(0)
	v_add_f32_e32 v0, v0, v14
	v_fmamk_f32 v0, v0, 0x3b000000, v212
	v_mul_f32_e32 v14, 0x4b800000, v0
	v_cmp_gt_f32_e32 vcc, s85, v0
	s_nop 1
	v_cndmask_b32_e32 v0, v0, v14, vcc
	v_rsq_f32_e32 v0, v0
	s_nop 0
	v_mul_f32_e32 v14, 0x45800000, v0
	v_cndmask_b32_e32 v0, v0, v14, vcc
	v_lshl_add_u64 v[14:15], s[26:27], 0, v[2:3]
	global_store_dword v[14:15], v0, off
.LBB0_741:
	s_or_b64 exec, exec, s[14:15]
	s_waitcnt lgkmcnt(0)
	v_lshl_add_u64 v[14:15], s[26:27], 0, v[4:5]
	s_waitcnt vmcnt(0)
	v_add_f32_e32 v0, 0, v34
	v_add_f32_e32 v0, v0, v35
	v_add_f32_e32 v0, v0, v36
	v_add_f32_e32 v0, v0, v37
	v_add_f32_e32 v0, v0, v38
	v_add_f32_e32 v0, v0, v39
	v_add_f32_e32 v0, v0, v40
	v_add_f32_e32 v0, v0, v41
	ds_bpermute_b32 v26, v18, v0
	s_waitcnt lgkmcnt(0)
	v_add_f32_e32 v26, v0, v26
	ds_bpermute_b32 v27, v19, v26
	s_waitcnt lgkmcnt(0)
	v_add_f32_e32 v26, v26, v27
	ds_bpermute_b32 v27, v20, v26
	s_waitcnt lgkmcnt(0)
	v_add_f32_e32 v26, v26, v27
	ds_bpermute_b32 v27, v21, v26
	s_waitcnt lgkmcnt(0)
	v_add_f32_e32 v26, v26, v27
	ds_bpermute_b32 v27, v22, v26
	s_waitcnt lgkmcnt(0)
	v_add_f32_e32 v26, v26, v27
	ds_bpermute_b32 v27, v23, v26
	s_waitcnt lgkmcnt(0)
	v_add_f32_e32 v26, v26, v27
	v_fmac_f32_e32 v0, 0xbc800000, v26
	v_mul_f32_e32 v26, v0, v0
	ds_bpermute_b32 v26, v18, v26
	s_waitcnt lgkmcnt(0)
	v_fmac_f32_e32 v26, v0, v0
	ds_bpermute_b32 v27, v19, v26
	s_waitcnt lgkmcnt(0)
	v_add_f32_e32 v26, v26, v27
	ds_bpermute_b32 v27, v20, v26
	s_waitcnt lgkmcnt(0)
	v_add_f32_e32 v26, v26, v27
	ds_bpermute_b32 v27, v21, v26
	s_waitcnt lgkmcnt(0)
	v_add_f32_e32 v26, v26, v27
	ds_bpermute_b32 v27, v22, v26
	s_waitcnt lgkmcnt(0)
	v_add_f32_e32 v26, v26, v27
	ds_bpermute_b32 v27, v23, v26
	s_waitcnt lgkmcnt(0)
	v_add_f32_e32 v26, v26, v27
	v_mov_b32_e32 v27, 0x3727c5ac
	v_fmamk_f32 v26, v26, 0x3c800000, v27
	v_cmp_gt_f32_e32 vcc, s85, v26
	v_mul_f32_e32 v27, 0x4b800000, v26
	s_nop 0
	v_cndmask_b32_e32 v26, v26, v27, vcc
	v_rsq_f32_e32 v26, v26
	s_nop 0
	v_mul_f32_e32 v27, 0x45800000, v26
	v_cndmask_b32_e32 v26, v26, v27, vcc
	v_mul_f32_e32 v0, v0, v26
	ds_bpermute_b32 v26, v20, v0
	s_and_saveexec_b64 s[14:15], s[2:3]
	s_cbranch_execz .LBB0_743
	s_mov_b32 s16, 0xfff0
	v_and_or_b32 v27, v25, s16, v24
	v_readlane_b32 s16, v249, 24
	v_lshlrev_b32_e32 v27, 2, v27
	v_readlane_b32 s17, v249, 25
	s_nop 4
	global_load_dword v28, v27, s[16:17] offset:32
	s_nop 0
	global_load_dword v27, v27, s[16:17]
	s_waitcnt vmcnt(1) lgkmcnt(0)
	v_mul_f32_e32 v26, v28, v26
	v_cndmask_b32_e64 v26, v26, -v26, s[6:7]
	s_waitcnt vmcnt(0)
	v_fmac_f32_e32 v26, v0, v27
	v_mov_b32_e32 v0, v26
.LBB0_743:
	s_or_b64 exec, exec, s[14:15]
	v_readlane_b32 s20, v252, 15
	v_readlane_b32 s26, v252, 21
	v_readlane_b32 s27, v252, 22
	v_cvt_pk_bf16_f32 v0, v0, v1
	v_readlane_b32 s21, v252, 16
	v_readlane_b32 s22, v252, 17
	s_waitcnt lgkmcnt(0)
	v_lshl_add_u64 v[26:27], s[26:27], 0, v[10:11]
	global_store_short v[26:27], v0, off
	v_readlane_b32 s23, v252, 18
	v_readlane_b32 s24, v252, 19
	v_readlane_b32 s25, v252, 20
	v_add_f32_e32 v0, 0, v42
	v_add_f32_e32 v0, v0, v43
	v_add_f32_e32 v0, v0, v44
	v_add_f32_e32 v0, v0, v45
	v_add_f32_e32 v0, v0, v46
	v_add_f32_e32 v0, v0, v47
	v_add_f32_e32 v0, v0, v48
	v_add_f32_e32 v0, v0, v49
	s_and_saveexec_b64 s[14:15], s[4:5]
	s_xor_b64 s[14:15], exec, s[14:15]
	s_cbranch_execz .LBB0_747
	s_and_saveexec_b64 s[16:17], s[8:9]
	s_cbranch_execz .LBB0_746
	v_mul_f32_e32 v0, 0xbfb8aa3b, v0
	v_exp_f32_e32 v0, v0
	v_readlane_b32 s20, v252, 15
	v_readlane_b32 s26, v252, 21
	v_readlane_b32 s27, v252, 22
	v_add_f32_e32 v0, 1.0, v0
	v_rcp_f32_e32 v0, v0
	v_lshl_add_u64 v[14:15], s[26:27], 0, v[8:9]
	v_readlane_b32 s21, v252, 16
	v_readlane_b32 s22, v252, 17
	v_readlane_b32 s23, v252, 18
	v_readlane_b32 s24, v252, 19
	v_readlane_b32 s25, v252, 20
	global_store_dword v[14:15], v0, off
